# grid barrier: acquire-side buffer_inv issued at arrival (latency overlaps the wait for release), on top of combined stack
# speedup vs baseline: 1.0163x; 1.0163x over previous
; __device__ __forceinline__ unsigned xb_ld(unsigned* p)              { return __hip_atomic_load(p, __ATOMIC_RELAXED, __HIP_MEMORY_SCOPE_AGENT); }
; __device__ __forceinline__ unsigned xb_add(unsigned* p, unsigned v) { return __hip_atomic_fetch_add(p, v, __ATOMIC_RELAXED, __HIP_MEMORY_SCOPE_AGENT); }
; #define XB_SPIN(cond, bar) do { unsigned _sp = 0; while (cond) { __builtin_amdgcn_s_sleep(1); \
;     if ((++_sp & 255u) == 0u) { if (xb_ld(&(bar)[XB_TMO])) break; if (_sp > XB_SPIN_CAP) { atomicAdd(&(bar)[XB_TMO], 1u); break; } } } } while (0)
; __device__ __forceinline__ void xcd_barrier(const XcdBarrier& b) {
;     ...
;         unsigned nloc = b.st[0], nx = b.st[1];
;         if (nloc == 0u) { xcd_barrier_complete(bar, b.x, nloc, nx); b.st[0] = nloc; b.st[1] = nx; }
;         const unsigned old = xb_add(&bar[XB_XSUB(b.x)], 1u);
;         const unsigned gen = old / nloc;
;         if (old + 1u == (gen + 1u) * nloc) {
;             __builtin_amdgcn_fence(__ATOMIC_RELEASE, "agent");
;             asm volatile("s_waitcnt vmcnt(0)" ::: "memory");
;             const unsigned og = xb_add(&bar[XB_TOP], 1u);
;             const unsigned tg = og / nx;
;             if (og + 1u == (tg + 1u) * nx) xb_add(&bar[XB_TOPGEN], 1u);
;             else XB_SPIN(xb_ld(&bar[XB_TOPGEN]) == tg, bar);
;             __builtin_amdgcn_fence(__ATOMIC_ACQUIRE, "agent");
;             xb_add(&bar[XB_XGEN(b.x)], 1u);
;             asm volatile("s_waitcnt vmcnt(0)" ::: "memory");
;         } else {
;             XB_SPIN(xb_ld(&bar[XB_XGEN(b.x)]) == gen, bar);
.LBB0_93:
	s_or_b64 exec, exec, s[18:19]
	v_cvt_f32_u32_e32 v4, v2
	s_waitcnt vmcnt(0)
	v_readfirstlane_b32 s2, v3
	v_sub_u32_e32 v3, 0, v2
	v_rcp_iflag_f32_e32 v4, v4
	v_add_u32_e32 v5, s2, v1
	v_mul_f32_e32 v4, 0x4f7ffffe, v4
	v_cvt_u32_f32_e32 v4, v4
	v_mul_lo_u32 v1, v3, v4
	v_mul_hi_u32 v1, v4, v1
	v_add_u32_e32 v1, v4, v1
	v_mul_hi_u32 v1, v5, v1
	v_mul_lo_u32 v3, v1, v2
	v_sub_u32_e32 v3, v5, v3
	v_add_u32_e32 v4, 1, v1
	v_cmp_ge_u32_e32 vcc, v3, v2
	s_nop 1
	v_cndmask_b32_e32 v1, v1, v4, vcc
	v_sub_u32_e32 v4, v3, v2
	v_cndmask_b32_e32 v3, v3, v4, vcc
	v_add_u32_e32 v4, 1, v1
	v_cmp_ge_u32_e32 vcc, v3, v2
	v_add_u32_e32 v3, 1, v5
	s_nop 0
	v_cndmask_b32_e32 v1, v1, v4, vcc
	v_mul_lo_u32 v4, v2, v1
	v_add_u32_e32 v2, v4, v2
	v_cmp_ne_u32_e32 vcc, v3, v2
	s_and_saveexec_b64 s[2:3], vcc
	s_xor_b64 s[14:15], exec, s[2:3]
	s_cbranch_execz .LBB0_107
	s_waitcnt lgkmcnt(0)
	buffer_inv sc1
	v_mov_b32_e32 v0, 0x2000
	global_load_dword v0, v0, s[8:9] offset:1024 sc1
	s_add_u32 s22, s8, 0x2400
	s_addc_u32 s23, s9, 0
	s_waitcnt vmcnt(0)
	v_cmp_eq_u32_e32 vcc, v0, v1
	s_and_saveexec_b64 s[18:19], vcc
	s_cbranch_execz .LBB0_106
	s_add_u32 s20, s6, 0x4200
	s_addc_u32 s21, s7, 0
	s_mov_b32 s2, 1
	s_mov_b64 s[24:25], 0
	v_mov_b32_e32 v0, 0
	s_branch .LBB0_97

; __device__ __forceinline__ unsigned xb_ld(unsigned* p)              { return __hip_atomic_load(p, __ATOMIC_RELAXED, __HIP_MEMORY_SCOPE_AGENT); }
; __device__ __forceinline__ unsigned xb_add(unsigned* p, unsigned v) { return __hip_atomic_fetch_add(p, v, __ATOMIC_RELAXED, __HIP_MEMORY_SCOPE_AGENT); }
; #define XB_SPIN(cond, bar) do { unsigned _sp = 0; while (cond) { __builtin_amdgcn_s_sleep(1); \
;     if ((++_sp & 255u) == 0u) { if (xb_ld(&(bar)[XB_TMO])) break; if (_sp > XB_SPIN_CAP) { atomicAdd(&(bar)[XB_TMO], 1u); break; } } } } while (0)
; __device__ __forceinline__ void xcd_barrier(const XcdBarrier& b) {
;     ...
;         if (old + 1u == (gen + 1u) * nloc) {
;             __builtin_amdgcn_fence(__ATOMIC_RELEASE, "agent");
;             asm volatile("s_waitcnt vmcnt(0)" ::: "memory");
;             const unsigned og = xb_add(&bar[XB_TOP], 1u);
;             const unsigned tg = og / nx;
;             if (og + 1u == (tg + 1u) * nx) xb_add(&bar[XB_TOPGEN], 1u);
;             else XB_SPIN(xb_ld(&bar[XB_TOPGEN]) == tg, bar);
;             __builtin_amdgcn_fence(__ATOMIC_ACQUIRE, "agent");
;             xb_add(&bar[XB_XGEN(b.x)], 1u);
;             asm volatile("s_waitcnt vmcnt(0)" ::: "memory");
;         } else {
;             XB_SPIN(xb_ld(&bar[XB_XGEN(b.x)]) == gen, bar);
;             __builtin_amdgcn_fence(__ATOMIC_ACQUIRE, "agent");
;             asm volatile("s_waitcnt vmcnt(0)" ::: "memory");
.LBB0_106:
	s_or_b64 exec, exec, s[18:19]
	s_waitcnt vmcnt(0)
	s_waitcnt vmcnt(0)
.LBB0_107:
	s_andn2_saveexec_b64 s[2:3], s[14:15]
	s_cbranch_execz .LBB0_127
	s_mov_b64 s[14:15], exec
	buffer_wbl2 sc1
	s_waitcnt lgkmcnt(0)
	s_waitcnt vmcnt(0)
	buffer_inv sc1
	v_mbcnt_lo_u32_b32 v1, s14, 0
	v_mbcnt_hi_u32_b32 v1, s15, v1
	v_cmp_eq_u32_e32 vcc, 0, v1
	s_and_saveexec_b64 s[18:19], vcc
	s_cbranch_execz .LBB0_110
	s_bcnt1_i32_b64 s2, s[14:15]
	v_mov_b32_e32 v2, 0x7000
	v_mov_b32_e32 v3, s2
	global_atomic_add v2, v2, v3, s[6:7] offset:1024 sc0

; __device__ __forceinline__ unsigned xb_ld(unsigned* p)              { return __hip_atomic_load(p, __ATOMIC_RELAXED, __HIP_MEMORY_SCOPE_AGENT); }
; __device__ __forceinline__ unsigned xb_add(unsigned* p, unsigned v) { return __hip_atomic_fetch_add(p, v, __ATOMIC_RELAXED, __HIP_MEMORY_SCOPE_AGENT); }
; #define XB_SPIN(cond, bar) do { unsigned _sp = 0; while (cond) { __builtin_amdgcn_s_sleep(1); \
;     if ((++_sp & 255u) == 0u) { if (xb_ld(&(bar)[XB_TMO])) break; if (_sp > XB_SPIN_CAP) { atomicAdd(&(bar)[XB_TMO], 1u); break; } } } } while (0)
; __device__ __forceinline__ void xcd_barrier(const XcdBarrier& b) {
;     ...
;             if (og + 1u == (tg + 1u) * nx) xb_add(&bar[XB_TOPGEN], 1u);
;             else XB_SPIN(xb_ld(&bar[XB_TOPGEN]) == tg, bar);
;             __builtin_amdgcn_fence(__ATOMIC_ACQUIRE, "agent");
;             xb_add(&bar[XB_XGEN(b.x)], 1u);
.LBB0_124:
	s_or_b64 exec, exec, s[6:7]
	s_mov_b64 s[6:7], exec
	v_mbcnt_lo_u32_b32 v0, s6, 0
	v_mbcnt_hi_u32_b32 v0, s7, v0
	v_cmp_eq_u32_e32 vcc, 0, v0
	s_waitcnt vmcnt(0)
	s_and_saveexec_b64 s[14:15], vcc
	s_cbranch_execz .LBB0_126
	s_bcnt1_i32_b64 s2, s[6:7]
	v_mov_b32_e32 v0, 0x2000
	v_mov_b32_e32 v1, s2
	global_atomic_add v0, v1, s[8:9] offset:1024

; __device__ __forceinline__ unsigned xb_ld(unsigned* p)              { return __hip_atomic_load(p, __ATOMIC_RELAXED, __HIP_MEMORY_SCOPE_AGENT); }
; __device__ __forceinline__ unsigned xb_add(unsigned* p, unsigned v) { return __hip_atomic_fetch_add(p, v, __ATOMIC_RELAXED, __HIP_MEMORY_SCOPE_AGENT); }
; #define XB_SPIN(cond, bar) do { unsigned _sp = 0; while (cond) { __builtin_amdgcn_s_sleep(1); \
;     if ((++_sp & 255u) == 0u) { if (xb_ld(&(bar)[XB_TMO])) break; if (_sp > XB_SPIN_CAP) { atomicAdd(&(bar)[XB_TMO], 1u); break; } } } } while (0)
; __device__ __forceinline__ void xcd_barrier(const XcdBarrier& b) {
;     ...
;         unsigned nloc = b.st[0], nx = b.st[1];
;         if (nloc == 0u) { xcd_barrier_complete(bar, b.x, nloc, nx); b.st[0] = nloc; b.st[1] = nx; }
;         const unsigned old = xb_add(&bar[XB_XSUB(b.x)], 1u);
;         const unsigned gen = old / nloc;
;         if (old + 1u == (gen + 1u) * nloc) {
;             __builtin_amdgcn_fence(__ATOMIC_RELEASE, "agent");
;             asm volatile("s_waitcnt vmcnt(0)" ::: "memory");
;             const unsigned og = xb_add(&bar[XB_TOP], 1u);
;             const unsigned tg = og / nx;
;             if (og + 1u == (tg + 1u) * nx) xb_add(&bar[XB_TOPGEN], 1u);
;             else XB_SPIN(xb_ld(&bar[XB_TOPGEN]) == tg, bar);
;             __builtin_amdgcn_fence(__ATOMIC_ACQUIRE, "agent");
;             xb_add(&bar[XB_XGEN(b.x)], 1u);
;             asm volatile("s_waitcnt vmcnt(0)" ::: "memory");
;         } else {
;             XB_SPIN(xb_ld(&bar[XB_XGEN(b.x)]) == gen, bar);
.LBB0_368:
	s_or_b64 exec, exec, s[14:15]
	v_cvt_f32_u32_e32 v5, v3
	s_waitcnt vmcnt(0)
	v_readfirstlane_b32 s2, v4
	v_sub_u32_e32 v4, 0, v3
	v_rcp_iflag_f32_e32 v5, v5
	v_add_u32_e32 v6, s2, v2
	v_mul_f32_e32 v5, 0x4f7ffffe, v5
	v_cvt_u32_f32_e32 v5, v5
	v_mul_lo_u32 v2, v4, v5
	v_mul_hi_u32 v2, v5, v2
	v_add_u32_e32 v2, v5, v2
	v_mul_hi_u32 v2, v6, v2
	v_mul_lo_u32 v4, v2, v3
	v_sub_u32_e32 v4, v6, v4
	v_add_u32_e32 v5, 1, v2
	v_cmp_ge_u32_e32 vcc, v4, v3
	s_nop 1
	v_cndmask_b32_e32 v2, v2, v5, vcc
	v_sub_u32_e32 v5, v4, v3
	v_cndmask_b32_e32 v4, v4, v5, vcc
	v_add_u32_e32 v5, 1, v2
	v_cmp_ge_u32_e32 vcc, v4, v3
	v_add_u32_e32 v4, 1, v6
	s_nop 0
	v_cndmask_b32_e32 v2, v2, v5, vcc
	v_mul_lo_u32 v5, v3, v2
	v_add_u32_e32 v3, v5, v3
	v_cmp_ne_u32_e32 vcc, v4, v3
	s_and_saveexec_b64 s[12:13], vcc
	s_xor_b64 s[12:13], exec, s[12:13]
	s_cbranch_execz .LBB0_382
	s_waitcnt lgkmcnt(0)
	buffer_inv sc1
	v_mov_b32_e32 v0, 0x2000
	global_load_dword v0, v0, s[8:9] offset:1024 sc1
	s_add_u32 s40, s8, 0x2400
	s_addc_u32 s41, s9, 0
	s_waitcnt vmcnt(0)
	v_cmp_eq_u32_e32 vcc, v0, v2
	s_and_saveexec_b64 s[14:15], vcc
	s_cbranch_execz .LBB0_381
	s_add_u32 s38, s6, 0x4200
	s_addc_u32 s39, s7, 0
	s_mov_b32 s2, 1
	s_mov_b64 s[42:43], 0
	s_branch .LBB0_372

; __device__ __forceinline__ unsigned xb_ld(unsigned* p)              { return __hip_atomic_load(p, __ATOMIC_RELAXED, __HIP_MEMORY_SCOPE_AGENT); }
; __device__ __forceinline__ unsigned xb_add(unsigned* p, unsigned v) { return __hip_atomic_fetch_add(p, v, __ATOMIC_RELAXED, __HIP_MEMORY_SCOPE_AGENT); }
; #define XB_SPIN(cond, bar) do { unsigned _sp = 0; while (cond) { __builtin_amdgcn_s_sleep(1); \
;     if ((++_sp & 255u) == 0u) { if (xb_ld(&(bar)[XB_TMO])) break; if (_sp > XB_SPIN_CAP) { atomicAdd(&(bar)[XB_TMO], 1u); break; } } } } while (0)
; __device__ __forceinline__ void xcd_barrier(const XcdBarrier& b) {
;     ...
;         if (old + 1u == (gen + 1u) * nloc) {
;             __builtin_amdgcn_fence(__ATOMIC_RELEASE, "agent");
;             asm volatile("s_waitcnt vmcnt(0)" ::: "memory");
;             const unsigned og = xb_add(&bar[XB_TOP], 1u);
;             const unsigned tg = og / nx;
;             if (og + 1u == (tg + 1u) * nx) xb_add(&bar[XB_TOPGEN], 1u);
;             else XB_SPIN(xb_ld(&bar[XB_TOPGEN]) == tg, bar);
;             __builtin_amdgcn_fence(__ATOMIC_ACQUIRE, "agent");
;             xb_add(&bar[XB_XGEN(b.x)], 1u);
;             asm volatile("s_waitcnt vmcnt(0)" ::: "memory");
;         } else {
;             XB_SPIN(xb_ld(&bar[XB_XGEN(b.x)]) == gen, bar);
;             __builtin_amdgcn_fence(__ATOMIC_ACQUIRE, "agent");
;             asm volatile("s_waitcnt vmcnt(0)" ::: "memory");
.LBB0_381:
	s_or_b64 exec, exec, s[14:15]
	s_waitcnt vmcnt(0)
	s_waitcnt vmcnt(0)
.LBB0_382:
	s_andn2_saveexec_b64 s[12:13], s[12:13]
	s_cbranch_execz .LBB0_402
	s_mov_b64 s[12:13], exec
	buffer_wbl2 sc1
	s_waitcnt lgkmcnt(0)
	s_waitcnt vmcnt(0)
	buffer_inv sc1
	v_mbcnt_lo_u32_b32 v2, s12, 0
	v_mbcnt_hi_u32_b32 v2, s13, v2
	v_cmp_eq_u32_e32 vcc, 0, v2
	s_and_saveexec_b64 s[14:15], vcc
	s_cbranch_execz .LBB0_385
	s_bcnt1_i32_b64 s2, s[12:13]
	v_mov_b32_e32 v3, s2
	v_mov_b32_e32 v4, 0x7000
	global_atomic_add v3, v4, v3, s[6:7] offset:1024 sc0

; __device__ __forceinline__ unsigned xb_ld(unsigned* p)              { return __hip_atomic_load(p, __ATOMIC_RELAXED, __HIP_MEMORY_SCOPE_AGENT); }
; __device__ __forceinline__ unsigned xb_add(unsigned* p, unsigned v) { return __hip_atomic_fetch_add(p, v, __ATOMIC_RELAXED, __HIP_MEMORY_SCOPE_AGENT); }
; #define XB_SPIN(cond, bar) do { unsigned _sp = 0; while (cond) { __builtin_amdgcn_s_sleep(1); \
;     if ((++_sp & 255u) == 0u) { if (xb_ld(&(bar)[XB_TMO])) break; if (_sp > XB_SPIN_CAP) { atomicAdd(&(bar)[XB_TMO], 1u); break; } } } } while (0)
; __device__ __forceinline__ void xcd_barrier(const XcdBarrier& b) {
;     ...
;             if (og + 1u == (tg + 1u) * nx) xb_add(&bar[XB_TOPGEN], 1u);
;             else XB_SPIN(xb_ld(&bar[XB_TOPGEN]) == tg, bar);
;             __builtin_amdgcn_fence(__ATOMIC_ACQUIRE, "agent");
;             xb_add(&bar[XB_XGEN(b.x)], 1u);
.LBB0_399:
	s_or_b64 exec, exec, s[6:7]
	s_mov_b64 s[6:7], exec
	v_mbcnt_lo_u32_b32 v0, s6, 0
	v_mbcnt_hi_u32_b32 v0, s7, v0
	v_cmp_eq_u32_e32 vcc, 0, v0
	s_waitcnt vmcnt(0)
	s_and_saveexec_b64 s[12:13], vcc
	s_cbranch_execz .LBB0_401
	s_bcnt1_i32_b64 s2, s[6:7]
	v_mov_b32_e32 v0, s2
	v_mov_b32_e32 v2, 0x2000
	global_atomic_add v2, v0, s[8:9] offset:1024

; __device__ __forceinline__ unsigned xb_ld(unsigned* p)              { return __hip_atomic_load(p, __ATOMIC_RELAXED, __HIP_MEMORY_SCOPE_AGENT); }
; __device__ __forceinline__ unsigned xb_add(unsigned* p, unsigned v) { return __hip_atomic_fetch_add(p, v, __ATOMIC_RELAXED, __HIP_MEMORY_SCOPE_AGENT); }
; #define XB_SPIN(cond, bar) do { unsigned _sp = 0; while (cond) { __builtin_amdgcn_s_sleep(1); \
;     if ((++_sp & 255u) == 0u) { if (xb_ld(&(bar)[XB_TMO])) break; if (_sp > XB_SPIN_CAP) { atomicAdd(&(bar)[XB_TMO], 1u); break; } } } } while (0)
; __device__ __forceinline__ void xcd_barrier(const XcdBarrier& b) {
;     ...
;         unsigned nloc = b.st[0], nx = b.st[1];
;         if (nloc == 0u) { xcd_barrier_complete(bar, b.x, nloc, nx); b.st[0] = nloc; b.st[1] = nx; }
;         const unsigned old = xb_add(&bar[XB_XSUB(b.x)], 1u);
;         const unsigned gen = old / nloc;
;         if (old + 1u == (gen + 1u) * nloc) {
;             __builtin_amdgcn_fence(__ATOMIC_RELEASE, "agent");
;             asm volatile("s_waitcnt vmcnt(0)" ::: "memory");
;             const unsigned og = xb_add(&bar[XB_TOP], 1u);
;             const unsigned tg = og / nx;
;             if (og + 1u == (tg + 1u) * nx) xb_add(&bar[XB_TOPGEN], 1u);
;             else XB_SPIN(xb_ld(&bar[XB_TOPGEN]) == tg, bar);
;             __builtin_amdgcn_fence(__ATOMIC_ACQUIRE, "agent");
;             xb_add(&bar[XB_XGEN(b.x)], 1u);
;             asm volatile("s_waitcnt vmcnt(0)" ::: "memory");
;         } else {
;             XB_SPIN(xb_ld(&bar[XB_XGEN(b.x)]) == gen, bar);
.LBB0_499:
	s_or_b64 exec, exec, s[40:41]
	v_cvt_f32_u32_e32 v5, v3
	s_waitcnt vmcnt(0)
	v_readfirstlane_b32 s2, v4
	v_sub_u32_e32 v4, 0, v3
	v_rcp_iflag_f32_e32 v5, v5
	v_add_u32_e32 v6, s2, v2
	v_mul_f32_e32 v5, 0x4f7ffffe, v5
	v_cvt_u32_f32_e32 v5, v5
	v_mul_lo_u32 v2, v4, v5
	v_mul_hi_u32 v2, v5, v2
	v_add_u32_e32 v2, v5, v2
	v_mul_hi_u32 v2, v6, v2
	v_mul_lo_u32 v4, v2, v3
	v_sub_u32_e32 v4, v6, v4
	v_add_u32_e32 v5, 1, v2
	v_cmp_ge_u32_e32 vcc, v4, v3
	s_nop 1
	v_cndmask_b32_e32 v2, v2, v5, vcc
	v_sub_u32_e32 v5, v4, v3
	v_cndmask_b32_e32 v4, v4, v5, vcc
	v_add_u32_e32 v5, 1, v2
	v_cmp_ge_u32_e32 vcc, v4, v3
	v_add_u32_e32 v4, 1, v6
	s_nop 0
	v_cndmask_b32_e32 v2, v2, v5, vcc
	v_mul_lo_u32 v5, v3, v2
	v_add_u32_e32 v3, v5, v3
	v_cmp_ne_u32_e32 vcc, v4, v3
	s_and_saveexec_b64 s[14:15], vcc
	s_xor_b64 s[14:15], exec, s[14:15]
	s_cbranch_execz .LBB0_513
	s_waitcnt lgkmcnt(0)
	buffer_inv sc1
	v_mov_b32_e32 v0, 0x2000
	global_load_dword v0, v0, s[12:13] offset:1024 sc1
	s_add_u32 s44, s12, 0x2400
	s_addc_u32 s45, s13, 0
	s_waitcnt vmcnt(0)
	v_cmp_eq_u32_e32 vcc, v0, v2
	s_and_saveexec_b64 s[40:41], vcc
	s_cbranch_execz .LBB0_512
	s_add_u32 s42, s8, 0x4200
	s_addc_u32 s43, s9, 0
	s_mov_b32 s2, 1
	s_mov_b64 s[46:47], 0
	s_branch .LBB0_503

; __device__ __forceinline__ unsigned xb_ld(unsigned* p)              { return __hip_atomic_load(p, __ATOMIC_RELAXED, __HIP_MEMORY_SCOPE_AGENT); }
; __device__ __forceinline__ unsigned xb_add(unsigned* p, unsigned v) { return __hip_atomic_fetch_add(p, v, __ATOMIC_RELAXED, __HIP_MEMORY_SCOPE_AGENT); }
; #define XB_SPIN(cond, bar) do { unsigned _sp = 0; while (cond) { __builtin_amdgcn_s_sleep(1); \
;     if ((++_sp & 255u) == 0u) { if (xb_ld(&(bar)[XB_TMO])) break; if (_sp > XB_SPIN_CAP) { atomicAdd(&(bar)[XB_TMO], 1u); break; } } } } while (0)
; __device__ __forceinline__ void xcd_barrier(const XcdBarrier& b) {
;     ...
;         if (old + 1u == (gen + 1u) * nloc) {
;             __builtin_amdgcn_fence(__ATOMIC_RELEASE, "agent");
;             asm volatile("s_waitcnt vmcnt(0)" ::: "memory");
;             const unsigned og = xb_add(&bar[XB_TOP], 1u);
;             const unsigned tg = og / nx;
;             if (og + 1u == (tg + 1u) * nx) xb_add(&bar[XB_TOPGEN], 1u);
;             else XB_SPIN(xb_ld(&bar[XB_TOPGEN]) == tg, bar);
;             __builtin_amdgcn_fence(__ATOMIC_ACQUIRE, "agent");
;             xb_add(&bar[XB_XGEN(b.x)], 1u);
;             asm volatile("s_waitcnt vmcnt(0)" ::: "memory");
;         } else {
;             XB_SPIN(xb_ld(&bar[XB_XGEN(b.x)]) == gen, bar);
;             __builtin_amdgcn_fence(__ATOMIC_ACQUIRE, "agent");
;             asm volatile("s_waitcnt vmcnt(0)" ::: "memory");
.LBB0_512:
	s_or_b64 exec, exec, s[40:41]
	s_waitcnt vmcnt(0)
	s_waitcnt vmcnt(0)
.LBB0_513:
	s_andn2_saveexec_b64 s[14:15], s[14:15]
	s_cbranch_execz .LBB0_533
	s_mov_b64 s[14:15], exec
	buffer_wbl2 sc1
	s_waitcnt lgkmcnt(0)
	s_waitcnt vmcnt(0)
	buffer_inv sc1
	v_mbcnt_lo_u32_b32 v2, s14, 0
	v_mbcnt_hi_u32_b32 v2, s15, v2
	v_cmp_eq_u32_e32 vcc, 0, v2
	s_and_saveexec_b64 s[40:41], vcc
	s_cbranch_execz .LBB0_516
	s_bcnt1_i32_b64 s2, s[14:15]
	v_mov_b32_e32 v3, s2
	v_mov_b32_e32 v4, 0x7000
	global_atomic_add v3, v4, v3, s[8:9] offset:1024 sc0

; __device__ __forceinline__ unsigned xb_ld(unsigned* p)              { return __hip_atomic_load(p, __ATOMIC_RELAXED, __HIP_MEMORY_SCOPE_AGENT); }
; __device__ __forceinline__ unsigned xb_add(unsigned* p, unsigned v) { return __hip_atomic_fetch_add(p, v, __ATOMIC_RELAXED, __HIP_MEMORY_SCOPE_AGENT); }
; #define XB_SPIN(cond, bar) do { unsigned _sp = 0; while (cond) { __builtin_amdgcn_s_sleep(1); \
;     if ((++_sp & 255u) == 0u) { if (xb_ld(&(bar)[XB_TMO])) break; if (_sp > XB_SPIN_CAP) { atomicAdd(&(bar)[XB_TMO], 1u); break; } } } } while (0)
; __device__ __forceinline__ void xcd_barrier(const XcdBarrier& b) {
;     ...
;             if (og + 1u == (tg + 1u) * nx) xb_add(&bar[XB_TOPGEN], 1u);
;             else XB_SPIN(xb_ld(&bar[XB_TOPGEN]) == tg, bar);
;             __builtin_amdgcn_fence(__ATOMIC_ACQUIRE, "agent");
;             xb_add(&bar[XB_XGEN(b.x)], 1u);
.LBB0_530:
	s_or_b64 exec, exec, s[8:9]
	s_mov_b64 s[8:9], exec
	v_mbcnt_lo_u32_b32 v0, s8, 0
	v_mbcnt_hi_u32_b32 v0, s9, v0
	v_cmp_eq_u32_e32 vcc, 0, v0
	s_waitcnt vmcnt(0)
	s_and_saveexec_b64 s[14:15], vcc
	s_cbranch_execz .LBB0_532
	s_bcnt1_i32_b64 s2, s[8:9]
	v_mov_b32_e32 v0, s2
	v_mov_b32_e32 v2, 0x2000
	global_atomic_add v2, v0, s[12:13] offset:1024

; __device__ __forceinline__ unsigned xb_ld(unsigned* p)              { return __hip_atomic_load(p, __ATOMIC_RELAXED, __HIP_MEMORY_SCOPE_AGENT); }
; __device__ __forceinline__ unsigned xb_add(unsigned* p, unsigned v) { return __hip_atomic_fetch_add(p, v, __ATOMIC_RELAXED, __HIP_MEMORY_SCOPE_AGENT); }
; #define XB_SPIN(cond, bar) do { unsigned _sp = 0; while (cond) { __builtin_amdgcn_s_sleep(1); \
;     if ((++_sp & 255u) == 0u) { if (xb_ld(&(bar)[XB_TMO])) break; if (_sp > XB_SPIN_CAP) { atomicAdd(&(bar)[XB_TMO], 1u); break; } } } } while (0)
; __device__ __forceinline__ void xcd_barrier(const XcdBarrier& b) {
;     ...
;         unsigned nloc = b.st[0], nx = b.st[1];
;         if (nloc == 0u) { xcd_barrier_complete(bar, b.x, nloc, nx); b.st[0] = nloc; b.st[1] = nx; }
;         const unsigned old = xb_add(&bar[XB_XSUB(b.x)], 1u);
;         const unsigned gen = old / nloc;
;         if (old + 1u == (gen + 1u) * nloc) {
;             __builtin_amdgcn_fence(__ATOMIC_RELEASE, "agent");
;             asm volatile("s_waitcnt vmcnt(0)" ::: "memory");
;             const unsigned og = xb_add(&bar[XB_TOP], 1u);
;             const unsigned tg = og / nx;
;             if (og + 1u == (tg + 1u) * nx) xb_add(&bar[XB_TOPGEN], 1u);
;             else XB_SPIN(xb_ld(&bar[XB_TOPGEN]) == tg, bar);
;             __builtin_amdgcn_fence(__ATOMIC_ACQUIRE, "agent");
;             xb_add(&bar[XB_XGEN(b.x)], 1u);
;             asm volatile("s_waitcnt vmcnt(0)" ::: "memory");
;         } else {
;             XB_SPIN(xb_ld(&bar[XB_XGEN(b.x)]) == gen, bar);
.LBB0_723:
	s_or_b64 exec, exec, s[38:39]
	v_cvt_f32_u32_e32 v5, v3
	s_waitcnt vmcnt(0)
	v_readfirstlane_b32 s2, v4
	v_sub_u32_e32 v4, 0, v3
	v_rcp_iflag_f32_e32 v5, v5
	v_add_u32_e32 v6, s2, v2
	v_mul_f32_e32 v5, 0x4f7ffffe, v5
	v_cvt_u32_f32_e32 v5, v5
	v_mul_lo_u32 v2, v4, v5
	v_mul_hi_u32 v2, v5, v2
	v_add_u32_e32 v2, v5, v2
	v_mul_hi_u32 v2, v6, v2
	v_mul_lo_u32 v4, v2, v3
	v_sub_u32_e32 v4, v6, v4
	v_add_u32_e32 v5, 1, v2
	v_cmp_ge_u32_e32 vcc, v4, v3
	s_nop 1
	v_cndmask_b32_e32 v2, v2, v5, vcc
	v_sub_u32_e32 v5, v4, v3
	v_cndmask_b32_e32 v4, v4, v5, vcc
	v_add_u32_e32 v5, 1, v2
	v_cmp_ge_u32_e32 vcc, v4, v3
	v_add_u32_e32 v4, 1, v6
	s_nop 0
	v_cndmask_b32_e32 v2, v2, v5, vcc
	v_mul_lo_u32 v5, v3, v2
	v_add_u32_e32 v3, v5, v3
	v_cmp_ne_u32_e32 vcc, v4, v3
	s_and_saveexec_b64 s[14:15], vcc
	s_xor_b64 s[14:15], exec, s[14:15]
	s_cbranch_execz .LBB0_737
	s_waitcnt lgkmcnt(0)
	buffer_inv sc1
	v_mov_b32_e32 v0, 0x2000
	global_load_dword v0, v0, s[12:13] offset:1024 sc1
	s_add_u32 s42, s12, 0x2400
	s_addc_u32 s43, s13, 0
	s_waitcnt vmcnt(0)
	v_cmp_eq_u32_e32 vcc, v0, v2
	s_and_saveexec_b64 s[38:39], vcc
	s_cbranch_execz .LBB0_736
	s_add_u32 s40, s8, 0x4200
	s_addc_u32 s41, s9, 0
	s_mov_b32 s2, 1
	s_mov_b64 s[44:45], 0
	s_branch .LBB0_727

; __device__ __forceinline__ unsigned xb_ld(unsigned* p)              { return __hip_atomic_load(p, __ATOMIC_RELAXED, __HIP_MEMORY_SCOPE_AGENT); }
; __device__ __forceinline__ unsigned xb_add(unsigned* p, unsigned v) { return __hip_atomic_fetch_add(p, v, __ATOMIC_RELAXED, __HIP_MEMORY_SCOPE_AGENT); }
; #define XB_SPIN(cond, bar) do { unsigned _sp = 0; while (cond) { __builtin_amdgcn_s_sleep(1); \
;     if ((++_sp & 255u) == 0u) { if (xb_ld(&(bar)[XB_TMO])) break; if (_sp > XB_SPIN_CAP) { atomicAdd(&(bar)[XB_TMO], 1u); break; } } } } while (0)
; __device__ __forceinline__ void xcd_barrier(const XcdBarrier& b) {
;     ...
;         if (old + 1u == (gen + 1u) * nloc) {
;             __builtin_amdgcn_fence(__ATOMIC_RELEASE, "agent");
;             asm volatile("s_waitcnt vmcnt(0)" ::: "memory");
;             const unsigned og = xb_add(&bar[XB_TOP], 1u);
;             const unsigned tg = og / nx;
;             if (og + 1u == (tg + 1u) * nx) xb_add(&bar[XB_TOPGEN], 1u);
;             else XB_SPIN(xb_ld(&bar[XB_TOPGEN]) == tg, bar);
;             __builtin_amdgcn_fence(__ATOMIC_ACQUIRE, "agent");
;             xb_add(&bar[XB_XGEN(b.x)], 1u);
;             asm volatile("s_waitcnt vmcnt(0)" ::: "memory");
;         } else {
;             XB_SPIN(xb_ld(&bar[XB_XGEN(b.x)]) == gen, bar);
;             __builtin_amdgcn_fence(__ATOMIC_ACQUIRE, "agent");
;             asm volatile("s_waitcnt vmcnt(0)" ::: "memory");
.LBB0_736:
	s_or_b64 exec, exec, s[38:39]
	s_waitcnt vmcnt(0)
	s_waitcnt vmcnt(0)
.LBB0_737:
	s_andn2_saveexec_b64 s[14:15], s[14:15]
	s_cbranch_execz .LBB0_757
	s_mov_b64 s[14:15], exec
	buffer_wbl2 sc1
	s_waitcnt lgkmcnt(0)
	s_waitcnt vmcnt(0)
	buffer_inv sc1
	v_mbcnt_lo_u32_b32 v2, s14, 0
	v_mbcnt_hi_u32_b32 v2, s15, v2
	v_cmp_eq_u32_e32 vcc, 0, v2
	s_and_saveexec_b64 s[38:39], vcc
	s_cbranch_execz .LBB0_740
	s_bcnt1_i32_b64 s2, s[14:15]
	v_mov_b32_e32 v3, s2
	v_mov_b32_e32 v4, 0x7000
	global_atomic_add v3, v4, v3, s[8:9] offset:1024 sc0

; __device__ __forceinline__ unsigned xb_ld(unsigned* p)              { return __hip_atomic_load(p, __ATOMIC_RELAXED, __HIP_MEMORY_SCOPE_AGENT); }
; __device__ __forceinline__ unsigned xb_add(unsigned* p, unsigned v) { return __hip_atomic_fetch_add(p, v, __ATOMIC_RELAXED, __HIP_MEMORY_SCOPE_AGENT); }
; #define XB_SPIN(cond, bar) do { unsigned _sp = 0; while (cond) { __builtin_amdgcn_s_sleep(1); \
;     if ((++_sp & 255u) == 0u) { if (xb_ld(&(bar)[XB_TMO])) break; if (_sp > XB_SPIN_CAP) { atomicAdd(&(bar)[XB_TMO], 1u); break; } } } } while (0)
; __device__ __forceinline__ void xcd_barrier(const XcdBarrier& b) {
;     ...
;         unsigned nloc = b.st[0], nx = b.st[1];
;         if (nloc == 0u) { xcd_barrier_complete(bar, b.x, nloc, nx); b.st[0] = nloc; b.st[1] = nx; }
;         const unsigned old = xb_add(&bar[XB_XSUB(b.x)], 1u);
;         const unsigned gen = old / nloc;
;         if (old + 1u == (gen + 1u) * nloc) {
;             __builtin_amdgcn_fence(__ATOMIC_RELEASE, "agent");
;             asm volatile("s_waitcnt vmcnt(0)" ::: "memory");
;             const unsigned og = xb_add(&bar[XB_TOP], 1u);
;             const unsigned tg = og / nx;
;             if (og + 1u == (tg + 1u) * nx) xb_add(&bar[XB_TOPGEN], 1u);
;             else XB_SPIN(xb_ld(&bar[XB_TOPGEN]) == tg, bar);
;             __builtin_amdgcn_fence(__ATOMIC_ACQUIRE, "agent");
;             xb_add(&bar[XB_XGEN(b.x)], 1u);
;             asm volatile("s_waitcnt vmcnt(0)" ::: "memory");
;         } else {
;             XB_SPIN(xb_ld(&bar[XB_XGEN(b.x)]) == gen, bar);
.LBB0_992:
	s_or_b64 exec, exec, s[10:11]
	v_cvt_f32_u32_e32 v4, v2
	s_waitcnt vmcnt(0)
	v_readfirstlane_b32 s8, v3
	v_sub_u32_e32 v3, 0, v2
	v_rcp_iflag_f32_e32 v4, v4
	v_add_u32_e32 v5, s8, v1
	v_mul_f32_e32 v4, 0x4f7ffffe, v4
	v_cvt_u32_f32_e32 v4, v4
	v_mul_lo_u32 v1, v3, v4
	v_mul_hi_u32 v1, v4, v1
	v_add_u32_e32 v1, v4, v1
	v_mul_hi_u32 v1, v5, v1
	v_mul_lo_u32 v3, v1, v2
	v_sub_u32_e32 v3, v5, v3
	v_add_u32_e32 v4, 1, v1
	v_cmp_ge_u32_e32 vcc, v3, v2
	s_nop 1
	v_cndmask_b32_e32 v1, v1, v4, vcc
	v_sub_u32_e32 v4, v3, v2
	v_cndmask_b32_e32 v3, v3, v4, vcc
	v_add_u32_e32 v4, 1, v1
	v_cmp_ge_u32_e32 vcc, v3, v2
	v_add_u32_e32 v3, 1, v5
	s_nop 0
	v_cndmask_b32_e32 v1, v1, v4, vcc
	v_mul_lo_u32 v4, v2, v1
	v_add_u32_e32 v2, v4, v2
	v_cmp_ne_u32_e32 vcc, v3, v2
	s_and_saveexec_b64 s[8:9], vcc
	s_xor_b64 s[8:9], exec, s[8:9]
	s_cbranch_execz .LBB0_1006
	s_waitcnt lgkmcnt(0)
	buffer_inv sc1
	v_mov_b32_e32 v0, 0x2000
	global_load_dword v0, v0, s[6:7] offset:1024 sc1
	s_add_u32 s14, s6, 0x2400
	s_addc_u32 s15, s7, 0
	s_waitcnt vmcnt(0)
	v_cmp_eq_u32_e32 vcc, v0, v1
	s_and_saveexec_b64 s[10:11], vcc
	s_cbranch_execz .LBB0_1005
	s_add_u32 s12, s4, 0x4200
	s_addc_u32 s13, s5, 0
	s_mov_b32 s26, 1
	s_mov_b64 s[16:17], 0
	v_mov_b32_e32 v0, 0
	s_branch .LBB0_996

; __device__ __forceinline__ unsigned xb_ld(unsigned* p)              { return __hip_atomic_load(p, __ATOMIC_RELAXED, __HIP_MEMORY_SCOPE_AGENT); }
; __device__ __forceinline__ unsigned xb_add(unsigned* p, unsigned v) { return __hip_atomic_fetch_add(p, v, __ATOMIC_RELAXED, __HIP_MEMORY_SCOPE_AGENT); }
; #define XB_SPIN(cond, bar) do { unsigned _sp = 0; while (cond) { __builtin_amdgcn_s_sleep(1); \
;     if ((++_sp & 255u) == 0u) { if (xb_ld(&(bar)[XB_TMO])) break; if (_sp > XB_SPIN_CAP) { atomicAdd(&(bar)[XB_TMO], 1u); break; } } } } while (0)
; __device__ __forceinline__ void xcd_barrier(const XcdBarrier& b) {
;     ...
;         if (old + 1u == (gen + 1u) * nloc) {
;             __builtin_amdgcn_fence(__ATOMIC_RELEASE, "agent");
;             asm volatile("s_waitcnt vmcnt(0)" ::: "memory");
;             const unsigned og = xb_add(&bar[XB_TOP], 1u);
;             const unsigned tg = og / nx;
;             if (og + 1u == (tg + 1u) * nx) xb_add(&bar[XB_TOPGEN], 1u);
;             else XB_SPIN(xb_ld(&bar[XB_TOPGEN]) == tg, bar);
;             __builtin_amdgcn_fence(__ATOMIC_ACQUIRE, "agent");
;             xb_add(&bar[XB_XGEN(b.x)], 1u);
;             asm volatile("s_waitcnt vmcnt(0)" ::: "memory");
;         } else {
;             XB_SPIN(xb_ld(&bar[XB_XGEN(b.x)]) == gen, bar);
;             __builtin_amdgcn_fence(__ATOMIC_ACQUIRE, "agent");
;             asm volatile("s_waitcnt vmcnt(0)" ::: "memory");
.LBB0_1005:
	s_or_b64 exec, exec, s[10:11]
	s_waitcnt vmcnt(0)
	s_waitcnt vmcnt(0)
.LBB0_1006:
	s_andn2_saveexec_b64 s[8:9], s[8:9]
	s_cbranch_execz .LBB0_1026
	s_mov_b64 s[8:9], exec
	buffer_wbl2 sc1
	s_waitcnt lgkmcnt(0)
	s_waitcnt vmcnt(0)
	buffer_inv sc1
	v_mbcnt_lo_u32_b32 v1, s8, 0
	v_mbcnt_hi_u32_b32 v1, s9, v1
	v_cmp_eq_u32_e32 vcc, 0, v1
	s_and_saveexec_b64 s[10:11], vcc
	s_cbranch_execz .LBB0_1009
	s_bcnt1_i32_b64 s8, s[8:9]
	v_mov_b32_e32 v2, 0x7000
	v_mov_b32_e32 v3, s8
	global_atomic_add v2, v2, v3, s[4:5] offset:1024 sc0

; __device__ __forceinline__ unsigned xb_ld(unsigned* p)              { return __hip_atomic_load(p, __ATOMIC_RELAXED, __HIP_MEMORY_SCOPE_AGENT); }
; __device__ __forceinline__ unsigned xb_add(unsigned* p, unsigned v) { return __hip_atomic_fetch_add(p, v, __ATOMIC_RELAXED, __HIP_MEMORY_SCOPE_AGENT); }
; #define XB_SPIN(cond, bar) do { unsigned _sp = 0; while (cond) { __builtin_amdgcn_s_sleep(1); \
;     if ((++_sp & 255u) == 0u) { if (xb_ld(&(bar)[XB_TMO])) break; if (_sp > XB_SPIN_CAP) { atomicAdd(&(bar)[XB_TMO], 1u); break; } } } } while (0)
; __device__ __forceinline__ void xcd_barrier(const XcdBarrier& b) {
;     ...
;             if (og + 1u == (tg + 1u) * nx) xb_add(&bar[XB_TOPGEN], 1u);
;             else XB_SPIN(xb_ld(&bar[XB_TOPGEN]) == tg, bar);
;             __builtin_amdgcn_fence(__ATOMIC_ACQUIRE, "agent");
;             xb_add(&bar[XB_XGEN(b.x)], 1u);
.LBB0_1023:
	s_or_b64 exec, exec, s[4:5]
	s_mov_b64 s[4:5], exec
	v_mbcnt_lo_u32_b32 v0, s4, 0
	v_mbcnt_hi_u32_b32 v0, s5, v0
	v_cmp_eq_u32_e32 vcc, 0, v0
	s_waitcnt vmcnt(0)
	s_and_saveexec_b64 s[8:9], vcc
	s_cbranch_execz .LBB0_1025
	s_bcnt1_i32_b64 s4, s[4:5]
	v_mov_b32_e32 v0, 0x2000
	v_mov_b32_e32 v1, s4
	global_atomic_add v0, v1, s[6:7] offset:1024
